# out-proj K-loop DMAs via scalar base too; no L2 writeback in the post-out-proj barrier (all its stores are write-through)
# baseline (speedup 1.0000x reference)
; #define PG8_STAGE(bufoff, gbase, voff) do { _Pragma("unroll") for (int _i = 0; _i < 2; ++_i) \
;         __builtin_amdgcn_global_load_lds((const unsigned*)((const char*)(gbase) + (voff)[_i]), (PG8_LAS unsigned*)(lds + (bufoff) + ldsw + _i * 8192), 16, 0, 0); } while (0)
; #define PG8_LDA(dst, b, h) do { _Pragma("unroll") for (int m = 0; m < 4; ++m) _Pragma("unroll") for (int k = 0; k < 2; ++k) dst[m][k] = *(const PG8_LAS bf16x8*)(lds + PG8_SA(b, h) + aoff + m * 2048 + k * 1024); } while (0)
; #define PG8_LDB(dst, b, h) do { _Pragma("unroll") for (int n = 0; n < 2; ++n) _Pragma("unroll") for (int k = 0; k < 2; ++k) dst[n][k] = *(const PG8_LAS bf16x8*)(lds + PG8_SB(b, h) + boff + n * 2048 + k * 1024); } while (0)
; #define PG8_MMA(ai, bj, At, Bt) do { __builtin_amdgcn_s_setprio(1); _Pragma("unroll") for (int m = 0; m < 4; ++m) _Pragma("unroll") for (int n = 0; n < 2; ++n) _Pragma("unroll") for (int k = 0; k < 2; ++k) \
;         acc[ai][bj][m][n] = __builtin_amdgcn_mfma_f32_16x16x32_bf16(Bt[n][k], At[m][k], acc[ai][bj][m][n], 0, 0, 0); __builtin_amdgcn_s_setprio(0); } while (0)
; #define PG8_WAIT_V(n) asm volatile("s_waitcnt vmcnt(" #n ")" ::: "memory")
; #define PG8_WAIT_L(n) asm volatile("s_waitcnt lgkmcnt(" #n ")" ::: "memory")
; template <class Epi, class Sched, bool ALIGN_EPI = false, bool SP2 = false>
; __device__ __forceinline__ void gemm_phase(PG8_LAS unsigned char* lds, const Gemm g, const Sched& S, const Epi& E) {
;     ...
;             const bool last = (t == nt - 2);
;             const char* a1 = cA + (size_t)(t + 1) * kstep;
;             const char* a2 = last ? nA : cA + (size_t)(t + 2) * kstep; const char* b2 = last ? nB : cB + (size_t)(t + 2) * kstep;
;             const char* a3 = a2 + kstep; const char* b3 = b2 + kstep;
;             if (last && has_next) S.a_ready(nxt);
;             if constexpr (SP2) {
;             PG8_LDB(B0, 0, 0); PG8_LDB(B1, 0, 1); PG8_SCHED; PG8_LDA(At, 0, 0); PG8_STAGE(PG8_SA(1, 1), a1 + hstep, voffA);
;             PG8_WAIT_V(8); PG8_WAIT_L(0); PG8_BAR; PG8_MMA(0, 0, At, B0); PG8_MMA(0, 1, At, B1); PG8_BAR; PG8_SCHED;
;             PG8_LDA(At, 0, 1); PG8_STAGE(PG8_SB(0, 0), b2, voffB); PG8_STAGE(PG8_SB(0, 1), b2 + hstep, voffB); PG8_STAGE(PG8_SA(0, 0), a2, voffA);
;             PG8_WAIT_V(8); PG8_WAIT_L(0); PG8_BAR; PG8_MMA(1, 0, At, B0); PG8_MMA(1, 1, At, B1); PG8_BAR; PG8_SCHED;
.LBB0_351:
	s_add_u32 s20, s8, 0xfffc0080
	s_addc_u32 s21, s9, -1
	s_add_i32 s80, 0, 0x10000
	s_cmp_eq_u32 s73, 12
	s_cselect_b32 s35, s17, s21
	s_cselect_b32 s34, s40, s20
	s_cselect_b32 s31, s13, s72
	s_cselect_b32 s30, s41, s58
	s_add_i32 s81, 0, 0x14000
	v_add_u32_e32 v148, s80, v153
	v_add_u32_e32 v168, s81, v153
	ds_read_b128 v[130:133], v148
	ds_read_b128 v[134:137], v148 offset:1024
	ds_read_b128 v[138:141], v148 offset:2048
	ds_read_b128 v[148:151], v148 offset:3072
	ds_read_b128 v[156:159], v168
	ds_read_b128 v[160:163], v168 offset:1024
	ds_read_b128 v[164:167], v168 offset:2048
	ds_read_b128 v[168:171], v168 offset:3072
	s_add_i32 m0, s43, 0xc000
	ds_read_b128 v[172:175], v155
	ds_read_b128 v[176:179], v155 offset:1024
	ds_read_b128 v[180:183], v155 offset:2048
	ds_read_b128 v[184:187], v155 offset:3072
	ds_read_b128 v[188:191], v155 offset:4096
	ds_read_b128 v[192:195], v155 offset:5120
	ds_read_b128 v[206:209], v155 offset:6144
	ds_read_b128 v[210:213], v155 offset:7168
	global_load_lds_dwordx4 v144, s[8:9]
	s_add_i32 m0, s43, 0xe000
	s_nop 0
	global_load_lds_dwordx4 v146, s[8:9]
	s_waitcnt vmcnt(8)
	s_waitcnt lgkmcnt(0)
	s_barrier
	s_setprio 1
	v_mfma_f32_16x16x32_bf16 v[126:129], v[130:133], v[172:175], v[126:129]
	v_mfma_f32_16x16x32_bf16 v[122:125], v[138:141], v[172:175], v[122:125]
	v_mfma_f32_16x16x32_bf16 v[118:121], v[130:133], v[180:183], v[118:121]
	v_mfma_f32_16x16x32_bf16 v[106:109], v[138:141], v[180:183], v[106:109]
	v_mfma_f32_16x16x32_bf16 v[102:105], v[130:133], v[188:191], v[102:105]
	v_mfma_f32_16x16x32_bf16 v[90:93], v[138:141], v[188:191], v[90:93]
	v_mfma_f32_16x16x32_bf16 v[86:89], v[130:133], v[206:209], v[86:89]
	v_mfma_f32_16x16x32_bf16 v[74:77], v[138:141], v[206:209], v[74:77]
	v_mfma_f32_16x16x32_bf16 v[126:129], v[134:137], v[176:179], v[126:129]
	v_mfma_f32_16x16x32_bf16 v[122:125], v[148:151], v[176:179], v[122:125]
	v_mfma_f32_16x16x32_bf16 v[118:121], v[134:137], v[184:187], v[118:121]
	v_mfma_f32_16x16x32_bf16 v[106:109], v[148:151], v[184:187], v[106:109]
	v_mfma_f32_16x16x32_bf16 v[102:105], v[134:137], v[192:195], v[102:105]
	v_mfma_f32_16x16x32_bf16 v[90:93], v[148:151], v[192:195], v[90:93]
	v_mfma_f32_16x16x32_bf16 v[86:89], v[134:137], v[210:213], v[86:89]
	v_mfma_f32_16x16x32_bf16 v[74:77], v[148:151], v[210:213], v[74:77]
	v_mfma_f32_16x16x32_bf16 v[114:117], v[156:159], v[172:175], v[114:117]
	v_mfma_f32_16x16x32_bf16 v[110:113], v[164:167], v[172:175], v[110:113]
	v_mfma_f32_16x16x32_bf16 v[98:101], v[156:159], v[180:183], v[98:101]
	v_mfma_f32_16x16x32_bf16 v[94:97], v[164:167], v[180:183], v[94:97]
	v_mfma_f32_16x16x32_bf16 v[82:85], v[156:159], v[188:191], v[82:85]
	v_mfma_f32_16x16x32_bf16 v[78:81], v[164:167], v[188:191], v[78:81]
	v_mfma_f32_16x16x32_bf16 v[70:73], v[156:159], v[206:209], v[70:73]
	v_mfma_f32_16x16x32_bf16 v[66:69], v[164:167], v[206:209], v[66:69]
	v_mfma_f32_16x16x32_bf16 v[114:117], v[160:163], v[176:179], v[114:117]
	v_mfma_f32_16x16x32_bf16 v[110:113], v[168:171], v[176:179], v[110:113]
	v_mfma_f32_16x16x32_bf16 v[98:101], v[160:163], v[184:187], v[98:101]
	v_mfma_f32_16x16x32_bf16 v[94:97], v[168:171], v[184:187], v[94:97]
	v_mfma_f32_16x16x32_bf16 v[82:85], v[160:163], v[192:195], v[82:85]
	v_mfma_f32_16x16x32_bf16 v[78:81], v[168:171], v[192:195], v[78:81]
	v_mfma_f32_16x16x32_bf16 v[70:73], v[160:163], v[210:213], v[70:73]
	v_mfma_f32_16x16x32_bf16 v[66:69], v[168:171], v[210:213], v[66:69]
	s_setprio 0
	s_barrier
	s_add_i32 s20, s80, s42
	s_mov_b32 m0, s20
	ds_read_b128 v[172:175], v155 offset:16384
	ds_read_b128 v[176:179], v155 offset:17408
	ds_read_b128 v[180:183], v155 offset:18432
	ds_read_b128 v[184:187], v155 offset:19456
	ds_read_b128 v[188:191], v155 offset:20480
	ds_read_b128 v[192:195], v155 offset:21504
	ds_read_b128 v[206:209], v155 offset:22528
	ds_read_b128 v[210:213], v155 offset:23552
	global_load_lds_dwordx4 v0, s[30:31]
	s_add_i32 m0, s20, 0x2000
	s_add_u32 s20, s30, 0x40000
	s_addc_u32 s21, s31, 0
	s_add_i32 s80, s81, s42
	global_load_lds_dwordx4 v142, s[30:31]
	s_mov_b32 m0, s80
	s_nop 0
	global_load_lds_dwordx4 v0, s[20:21]
	s_add_i32 m0, s80, 0x2000
	s_nop 0
	global_load_lds_dwordx4 v142, s[20:21]
	s_mov_b32 m0, s43
	s_nop 0
	global_load_lds_dwordx4 v0, s[34:35]
	s_mov_b32 m0, s46
	s_nop 0
	global_load_lds_dwordx4 v142, s[34:35]
	s_waitcnt vmcnt(8)
	s_waitcnt lgkmcnt(0)
	s_barrier
	s_setprio 1
	v_mfma_f32_16x16x32_bf16 v[62:65], v[130:133], v[172:175], v[62:65]
	v_mfma_f32_16x16x32_bf16 v[58:61], v[138:141], v[172:175], v[58:61]
	v_mfma_f32_16x16x32_bf16 v[54:57], v[130:133], v[180:183], v[54:57]
	v_mfma_f32_16x16x32_bf16 v[42:45], v[138:141], v[180:183], v[42:45]
	v_mfma_f32_16x16x32_bf16 v[38:41], v[130:133], v[188:191], v[38:41]
	v_mfma_f32_16x16x32_bf16 v[26:29], v[138:141], v[188:191], v[26:29]
	v_mfma_f32_16x16x32_bf16 v[18:21], v[130:133], v[206:209], v[18:21]
	v_mfma_f32_16x16x32_bf16 v[10:13], v[138:141], v[206:209], v[10:13]
	v_mfma_f32_16x16x32_bf16 v[62:65], v[134:137], v[176:179], v[62:65]
	v_mfma_f32_16x16x32_bf16 v[58:61], v[148:151], v[176:179], v[58:61]
	v_mfma_f32_16x16x32_bf16 v[54:57], v[134:137], v[184:187], v[54:57]
	v_mfma_f32_16x16x32_bf16 v[42:45], v[148:151], v[184:187], v[42:45]
	v_mfma_f32_16x16x32_bf16 v[38:41], v[134:137], v[192:195], v[38:41]
	v_mfma_f32_16x16x32_bf16 v[26:29], v[148:151], v[192:195], v[26:29]
	v_mfma_f32_16x16x32_bf16 v[18:21], v[134:137], v[210:213], v[18:21]
	v_mfma_f32_16x16x32_bf16 v[10:13], v[148:151], v[210:213], v[10:13]
	v_mfma_f32_16x16x32_bf16 v[50:53], v[156:159], v[172:175], v[50:53]
	v_mfma_f32_16x16x32_bf16 v[46:49], v[164:167], v[172:175], v[46:49]
	v_mfma_f32_16x16x32_bf16 v[34:37], v[156:159], v[180:183], v[34:37]
	v_mfma_f32_16x16x32_bf16 v[30:33], v[164:167], v[180:183], v[30:33]
	v_mfma_f32_16x16x32_bf16 v[22:25], v[156:159], v[188:191], v[22:25]
	v_mfma_f32_16x16x32_bf16 v[14:17], v[164:167], v[188:191], v[14:17]
	v_mfma_f32_16x16x32_bf16 v[6:9], v[156:159], v[206:209], v[6:9]
	v_mfma_f32_16x16x32_bf16 v[2:5], v[164:167], v[206:209], v[2:5]
	v_mfma_f32_16x16x32_bf16 v[50:53], v[160:163], v[176:179], v[50:53]
	v_mfma_f32_16x16x32_bf16 v[46:49], v[168:171], v[176:179], v[46:49]
	v_mfma_f32_16x16x32_bf16 v[34:37], v[160:163], v[184:187], v[34:37]
	v_mfma_f32_16x16x32_bf16 v[30:33], v[168:171], v[184:187], v[30:33]
	v_mfma_f32_16x16x32_bf16 v[22:25], v[160:163], v[192:195], v[22:25]
	v_mfma_f32_16x16x32_bf16 v[14:17], v[168:171], v[192:195], v[14:17]
	v_mfma_f32_16x16x32_bf16 v[6:9], v[160:163], v[210:213], v[6:9]
	v_mfma_f32_16x16x32_bf16 v[2:5], v[168:171], v[210:213], v[2:5]
	s_setprio 0
	s_barrier
; #define PG8_STAGE(bufoff, gbase, voff) do { _Pragma("unroll") for (int _i = 0; _i < 2; ++_i) \
;         __builtin_amdgcn_global_load_lds((const unsigned*)((const char*)(gbase) + (voff)[_i]), (PG8_LAS unsigned*)(lds + (bufoff) + ldsw + _i * 8192), 16, 0, 0); } while (0)
; #define PG8_LDA(dst, b, h) do { _Pragma("unroll") for (int m = 0; m < 4; ++m) _Pragma("unroll") for (int k = 0; k < 2; ++k) dst[m][k] = *(const PG8_LAS bf16x8*)(lds + PG8_SA(b, h) + aoff + m * 2048 + k * 1024); } while (0)
; #define PG8_LDB(dst, b, h) do { _Pragma("unroll") for (int n = 0; n < 2; ++n) _Pragma("unroll") for (int k = 0; k < 2; ++k) dst[n][k] = *(const PG8_LAS bf16x8*)(lds + PG8_SB(b, h) + boff + n * 2048 + k * 1024); } while (0)
; #define PG8_MMA(ai, bj, At, Bt) do { __builtin_amdgcn_s_setprio(1); _Pragma("unroll") for (int m = 0; m < 4; ++m) _Pragma("unroll") for (int n = 0; n < 2; ++n) _Pragma("unroll") for (int k = 0; k < 2; ++k) \
;         acc[ai][bj][m][n] = __builtin_amdgcn_mfma_f32_16x16x32_bf16(Bt[n][k], At[m][k], acc[ai][bj][m][n], 0, 0, 0); __builtin_amdgcn_s_setprio(0); } while (0)
; #define PG8_WAIT_V(n) asm volatile("s_waitcnt vmcnt(" #n ")" ::: "memory")
; #define PG8_WAIT_L(n) asm volatile("s_waitcnt lgkmcnt(" #n ")" ::: "memory")
; #define PG8_BAR __builtin_amdgcn_s_barrier()
; #define PG8_SCHED __builtin_amdgcn_sched_barrier(0)
; template <class Epi, class Sched, bool ALIGN_EPI = false, bool SP2 = false>
; __device__ __forceinline__ void gemm_phase(PG8_LAS unsigned char* lds, const Gemm g, const Sched& S, const Epi& E) {
;     ...
;             PG8_LDB(B0, 1, 0); PG8_LDB(B1, 1, 1); PG8_SCHED; PG8_LDA(At, 1, 0); PG8_STAGE(PG8_SA(0, 1), a2 + hstep, voffA);
;             PG8_WAIT_V(8); PG8_WAIT_L(0); PG8_BAR; PG8_MMA(0, 0, At, B0); PG8_MMA(0, 1, At, B1); PG8_BAR; PG8_SCHED;
;             PG8_LDA(At, 1, 1); PG8_STAGE(PG8_SB(1, 0), b3, voffB); PG8_STAGE(PG8_SB(1, 1), b3 + hstep, voffB); PG8_STAGE(PG8_SA(1, 0), a3, voffA);
;             PG8_WAIT_V(8); PG8_WAIT_L(0); PG8_BAR; PG8_MMA(1, 0, At, B0); PG8_MMA(1, 1, At, B1); PG8_BAR; PG8_SCHED;
	s_add_i32 s80, 0, 0x18000
	s_add_i32 s81, 0, 0x1c000
	v_add_u32_e32 v148, s80, v153
	v_add_u32_e32 v168, s81, v153
	ds_read_b128 v[130:133], v148
	ds_read_b128 v[134:137], v148 offset:1024
	ds_read_b128 v[138:141], v148 offset:2048
	ds_read_b128 v[148:151], v148 offset:3072
	ds_read_b128 v[156:159], v168
	ds_read_b128 v[160:163], v168 offset:1024
	ds_read_b128 v[164:167], v168 offset:2048
	ds_read_b128 v[168:171], v168 offset:3072
	s_add_u32 s20, s34, 0x40000
	s_addc_u32 s21, s35, 0
	s_mov_b32 m0, s47
	ds_read_b128 v[172:175], v155 offset:32768
	ds_read_b128 v[176:179], v155 offset:33792
	ds_read_b128 v[180:183], v155 offset:34816
	ds_read_b128 v[184:187], v155 offset:35840
	ds_read_b128 v[188:191], v155 offset:36864
	ds_read_b128 v[192:195], v155 offset:37888
	ds_read_b128 v[206:209], v155 offset:38912
	ds_read_b128 v[210:213], v155 offset:39936
	global_load_lds_dwordx4 v0, s[20:21]
	s_mov_b32 m0, s52
	s_nop 0
	global_load_lds_dwordx4 v142, s[20:21]
	s_waitcnt vmcnt(8)
	s_waitcnt lgkmcnt(0)
	s_barrier
	s_setprio 1
	v_mfma_f32_16x16x32_bf16 v[126:129], v[130:133], v[172:175], v[126:129]
	v_mfma_f32_16x16x32_bf16 v[122:125], v[138:141], v[172:175], v[122:125]
	v_mfma_f32_16x16x32_bf16 v[118:121], v[130:133], v[180:183], v[118:121]
	v_mfma_f32_16x16x32_bf16 v[106:109], v[138:141], v[180:183], v[106:109]
	v_mfma_f32_16x16x32_bf16 v[102:105], v[130:133], v[188:191], v[102:105]
	v_mfma_f32_16x16x32_bf16 v[90:93], v[138:141], v[188:191], v[90:93]
	v_mfma_f32_16x16x32_bf16 v[86:89], v[130:133], v[206:209], v[86:89]
	v_mfma_f32_16x16x32_bf16 v[74:77], v[138:141], v[206:209], v[74:77]
	v_mfma_f32_16x16x32_bf16 v[126:129], v[134:137], v[176:179], v[126:129]
	v_mfma_f32_16x16x32_bf16 v[122:125], v[148:151], v[176:179], v[122:125]
	v_mfma_f32_16x16x32_bf16 v[118:121], v[134:137], v[184:187], v[118:121]
	v_mfma_f32_16x16x32_bf16 v[106:109], v[148:151], v[184:187], v[106:109]
	v_mfma_f32_16x16x32_bf16 v[102:105], v[134:137], v[192:195], v[102:105]
	v_mfma_f32_16x16x32_bf16 v[90:93], v[148:151], v[192:195], v[90:93]
	v_mfma_f32_16x16x32_bf16 v[86:89], v[134:137], v[210:213], v[86:89]
	v_mfma_f32_16x16x32_bf16 v[74:77], v[148:151], v[210:213], v[74:77]
	v_mfma_f32_16x16x32_bf16 v[114:117], v[156:159], v[172:175], v[114:117]
	v_mfma_f32_16x16x32_bf16 v[110:113], v[164:167], v[172:175], v[110:113]
	v_mfma_f32_16x16x32_bf16 v[98:101], v[156:159], v[180:183], v[98:101]
	v_mfma_f32_16x16x32_bf16 v[94:97], v[164:167], v[180:183], v[94:97]
	v_mfma_f32_16x16x32_bf16 v[82:85], v[156:159], v[188:191], v[82:85]
	v_mfma_f32_16x16x32_bf16 v[78:81], v[164:167], v[188:191], v[78:81]
	v_mfma_f32_16x16x32_bf16 v[70:73], v[156:159], v[206:209], v[70:73]
	v_mfma_f32_16x16x32_bf16 v[66:69], v[164:167], v[206:209], v[66:69]
	v_mfma_f32_16x16x32_bf16 v[114:117], v[160:163], v[176:179], v[114:117]
	v_mfma_f32_16x16x32_bf16 v[110:113], v[168:171], v[176:179], v[110:113]
	v_mfma_f32_16x16x32_bf16 v[98:101], v[160:163], v[184:187], v[98:101]
	v_mfma_f32_16x16x32_bf16 v[94:97], v[168:171], v[184:187], v[94:97]
	v_mfma_f32_16x16x32_bf16 v[82:85], v[160:163], v[192:195], v[82:85]
	v_mfma_f32_16x16x32_bf16 v[78:81], v[168:171], v[192:195], v[78:81]
	v_mfma_f32_16x16x32_bf16 v[70:73], v[160:163], v[210:213], v[70:73]
	v_mfma_f32_16x16x32_bf16 v[66:69], v[168:171], v[210:213], v[66:69]
	s_setprio 0
	s_barrier
	s_add_i32 s20, s80, s42
	s_add_i32 m0, s20, 0xffffff80
	ds_read_b128 v[172:175], v155 offset:49152
	ds_read_b128 v[176:179], v155 offset:50176
	ds_read_b128 v[180:183], v155 offset:51200
	ds_read_b128 v[184:187], v155 offset:52224
	ds_read_b128 v[188:191], v155 offset:53248
	ds_read_b128 v[192:195], v155 offset:54272
	ds_read_b128 v[206:209], v155 offset:55296
	ds_read_b128 v[210:213], v155 offset:56320
	global_load_lds_dwordx4 v0, s[30:31] offset:128
	s_add_i32 m0, s20, 0x1f80
	s_add_u32 s20, s30, 0x40080
	s_addc_u32 s21, s31, 0
	global_load_lds_dwordx4 v142, s[30:31] offset:128
	s_add_i32 s30, s81, s42
	s_mov_b32 m0, s30
	s_nop 0
	global_load_lds_dwordx4 v0, s[20:21]
	s_add_i32 m0, s30, 0x2000
	s_nop 0
	global_load_lds_dwordx4 v142, s[20:21]
	s_add_i32 m0, s53, 0xffffff80
	s_nop 0
	global_load_lds_dwordx4 v0, s[34:35] offset:128
	s_add_i32 m0, s55, 0xffffff80
	s_nop 0
	global_load_lds_dwordx4 v142, s[34:35] offset:128
	s_waitcnt vmcnt(8)
	s_waitcnt lgkmcnt(0)
	s_barrier
	s_setprio 1
	v_mfma_f32_16x16x32_bf16 v[62:65], v[130:133], v[172:175], v[62:65]
	v_mfma_f32_16x16x32_bf16 v[58:61], v[138:141], v[172:175], v[58:61]
	v_mfma_f32_16x16x32_bf16 v[54:57], v[130:133], v[180:183], v[54:57]
	v_mfma_f32_16x16x32_bf16 v[42:45], v[138:141], v[180:183], v[42:45]
	v_mfma_f32_16x16x32_bf16 v[38:41], v[130:133], v[188:191], v[38:41]
	v_mfma_f32_16x16x32_bf16 v[26:29], v[138:141], v[188:191], v[26:29]
	v_mfma_f32_16x16x32_bf16 v[18:21], v[130:133], v[206:209], v[18:21]
	v_mfma_f32_16x16x32_bf16 v[10:13], v[138:141], v[206:209], v[10:13]
	v_mfma_f32_16x16x32_bf16 v[62:65], v[134:137], v[176:179], v[62:65]
	v_mfma_f32_16x16x32_bf16 v[58:61], v[148:151], v[176:179], v[58:61]
	v_mfma_f32_16x16x32_bf16 v[54:57], v[134:137], v[184:187], v[54:57]
	v_mfma_f32_16x16x32_bf16 v[42:45], v[148:151], v[184:187], v[42:45]
	v_mfma_f32_16x16x32_bf16 v[38:41], v[134:137], v[192:195], v[38:41]
	v_mfma_f32_16x16x32_bf16 v[26:29], v[148:151], v[192:195], v[26:29]
	v_mfma_f32_16x16x32_bf16 v[18:21], v[134:137], v[210:213], v[18:21]
	v_mfma_f32_16x16x32_bf16 v[10:13], v[148:151], v[210:213], v[10:13]
	v_mfma_f32_16x16x32_bf16 v[50:53], v[156:159], v[172:175], v[50:53]
	v_mfma_f32_16x16x32_bf16 v[46:49], v[164:167], v[172:175], v[46:49]
	v_mfma_f32_16x16x32_bf16 v[34:37], v[156:159], v[180:183], v[34:37]
	v_mfma_f32_16x16x32_bf16 v[30:33], v[164:167], v[180:183], v[30:33]
	v_mfma_f32_16x16x32_bf16 v[22:25], v[156:159], v[188:191], v[22:25]
	v_mfma_f32_16x16x32_bf16 v[14:17], v[164:167], v[188:191], v[14:17]
	v_mfma_f32_16x16x32_bf16 v[6:9], v[156:159], v[206:209], v[6:9]
	v_mfma_f32_16x16x32_bf16 v[2:5], v[164:167], v[206:209], v[2:5]
	v_mfma_f32_16x16x32_bf16 v[50:53], v[160:163], v[176:179], v[50:53]
	v_mfma_f32_16x16x32_bf16 v[46:49], v[168:171], v[176:179], v[46:49]
	v_mfma_f32_16x16x32_bf16 v[34:37], v[160:163], v[184:187], v[34:37]
	v_mfma_f32_16x16x32_bf16 v[30:33], v[168:171], v[184:187], v[30:33]
	v_mfma_f32_16x16x32_bf16 v[22:25], v[160:163], v[192:195], v[22:25]
	v_mfma_f32_16x16x32_bf16 v[14:17], v[168:171], v[192:195], v[14:17]
	v_mfma_f32_16x16x32_bf16 v[6:9], v[160:163], v[210:213], v[6:9]
	v_mfma_f32_16x16x32_bf16 v[2:5], v[168:171], v[210:213], v[2:5]
	s_setprio 0
	s_barrier
	s_add_i32 s73, s73, 2
	s_add_u32 s8, s8, 0x100
	s_addc_u32 s9, s9, 0
	s_add_u32 s58, s58, 0x100
	s_addc_u32 s72, s72, 0
	s_cmp_gt_u32 s73, 13
	s_cbranch_scc0 .LBB0_351
	s_and_b64 vcc, exec, s[10:11]
	s_cbranch_vccz .LBB0_354
	s_barrier

; __device__ __forceinline__ unsigned xb_add(unsigned* p, unsigned v) { return __hip_atomic_fetch_add(p, v, __ATOMIC_RELAXED, __HIP_MEMORY_SCOPE_AGENT); }
; __device__ __forceinline__ void xcd_barrier(const XcdBarrier& b) {
;     ...
;         if (old + 1u == (gen + 1u) * nloc) {
;             __builtin_amdgcn_fence(__ATOMIC_RELEASE, "agent");
;             asm volatile("s_waitcnt vmcnt(0)" ::: "memory");
;             const unsigned og = xb_add(&bar[XB_TOP], 1u);
;             const unsigned tg = og / nx;
;             if (og + 1u == (tg + 1u) * nx) xb_add(&bar[XB_TOPGEN], 1u);
.LBB0_390:
	s_andn2_saveexec_b64 s[6:7], s[6:7]
	s_cbranch_execz .LBB0_36
	s_mov_b64 s[6:7], exec
	s_waitcnt lgkmcnt(0)
	s_waitcnt vmcnt(0)
	v_mbcnt_lo_u32_b32 v0, s6, 0
	v_mbcnt_hi_u32_b32 v0, s7, v0
	v_cmp_eq_u32_e32 vcc, 0, v0
	s_and_saveexec_b64 s[8:9], vcc
	s_cbranch_execz .LBB0_393
	s_bcnt1_i32_b64 s6, s[6:7]
	v_mov_b32_e32 v3, s6
	v_readlane_b32 s6, v254, 58
	v_readlane_b32 s7, v254, 59
	s_nop 4
	global_atomic_add v3, v1, v3, s[6:7] sc0
